# v35 + grid barrier release: last XCD leader bumps every XCD's generation word directly; leaders poll their own XGEN (TOPGEN hop removed)
# speedup vs baseline: 1.0036x; 1.0036x over previous
.LBB0_270:
	s_or_b64 exec, exec, s[2:3]
	s_waitcnt vmcnt(0)
	s_waitcnt vmcnt(0)

.LBB0_428:
	s_or_b64 exec, exec, s[4:5]
	s_waitcnt vmcnt(0)
	v_readfirstlane_b32 s2, v2
	v_cvt_f32_u32_e32 v2, v0
	v_sub_u32_e32 v3, 0, v0
	v_add_u32_e32 v1, s2, v1
	v_readlane_b32 s2, v242, 52
	v_rcp_iflag_f32_e32 v2, v2
	v_readlane_b32 s3, v242, 53
	s_mov_b64 s[4:5], -1
	v_mul_f32_e32 v2, 0x4f7ffffe, v2
	v_cvt_u32_f32_e32 v2, v2
	v_mul_lo_u32 v3, v3, v2
	v_mul_hi_u32 v3, v2, v3
	v_add_u32_e32 v2, v2, v3
	v_mul_hi_u32 v2, v1, v2
	v_mul_lo_u32 v3, v2, v0
	v_sub_u32_e32 v3, v1, v3
	v_cmp_ge_u32_e32 vcc, v3, v0
	v_add_u32_e32 v4, 1, v2
	v_add_u32_e32 v1, 1, v1
	v_cndmask_b32_e32 v2, v2, v4, vcc
	v_sub_u32_e32 v4, v3, v0
	v_cndmask_b32_e32 v3, v3, v4, vcc
	v_cmp_ge_u32_e32 vcc, v3, v0
	v_add_u32_e32 v3, 1, v2
	s_nop 0
	v_cndmask_b32_e32 v2, v2, v3, vcc
	v_mul_lo_u32 v3, v0, v2
	v_add_u32_e32 v0, v3, v0
	v_cmp_ne_u32_e32 vcc, v1, v0
	v_mov_b64_e32 v[0:1], s[2:3]
	s_and_saveexec_b64 s[2:3], vcc
	s_cbranch_execz .LBB0_440
	v_readlane_b32 s4, v242, 52
	v_readlane_b32 s5, v242, 53
	s_mov_b64 s[6:7], 0
	s_nop 3
	global_load_dword v0, v[142:143], off sc1
	s_waitcnt vmcnt(0)
	v_cmp_eq_u32_e32 vcc, v0, v2
	s_and_saveexec_b64 s[4:5], vcc
	s_cbranch_execz .LBB0_439
	s_mov_b32 s12, 1
	s_branch .LBB0_432

.LBB0_434:
	v_readlane_b32 s10, v242, 52
	v_readlane_b32 s11, v242, 53
	s_add_i32 s12, s12, 1
	s_mov_b64 s[14:15], -1
	s_nop 2
	global_load_dword v0, v[142:143], off sc1
	s_waitcnt vmcnt(0)
	v_cmp_ne_u32_e32 vcc, v0, v2
	s_orn2_b64 s[10:11], vcc, exec
	s_branch .LBB0_431

.LBB0_440:
	s_or_b64 exec, exec, s[2:3]
	s_and_saveexec_b64 s[2:3], s[4:5]
	s_cbranch_execz .LBB0_442
	v_readlane_b32 s4, v242, 50
	v_readlane_b32 s5, v242, 51
	s_nop 4
	global_atomic_add v129, v166, s[4:5] offset:-4096
	global_atomic_add v129, v166, s[4:5] offset:-3840
	global_atomic_add v129, v166, s[4:5] offset:-3584
	global_atomic_add v129, v166, s[4:5] offset:-3328
	global_atomic_add v129, v166, s[4:5] offset:-3072
	global_atomic_add v129, v166, s[4:5] offset:-2816
	global_atomic_add v129, v166, s[4:5] offset:-2560
	global_atomic_add v129, v166, s[4:5] offset:-2304
	global_atomic_add v129, v166, s[4:5] offset:-2048
	global_atomic_add v129, v166, s[4:5] offset:-1792
	global_atomic_add v129, v166, s[4:5] offset:-1536
	global_atomic_add v129, v166, s[4:5] offset:-1280
	global_atomic_add v129, v166, s[4:5] offset:-1024
	global_atomic_add v129, v166, s[4:5] offset:-768
	global_atomic_add v129, v166, s[4:5] offset:-512
	global_atomic_add v129, v166, s[4:5] offset:-256

.Ltramp_270:
	s_branch .LBB0_270
.Ltramp_271:
	s_branch .LBB0_271

.LBB0_1410:
	s_or_b64 exec, exec, s[6:7]
	s_waitcnt vmcnt(0)
	v_readfirstlane_b32 s1, v2
	v_cvt_f32_u32_e32 v2, v0
	v_sub_u32_e32 v3, 0, v0
	v_add_u32_e32 v1, s1, v1
	v_readlane_b32 s4, v242, 52
	v_rcp_iflag_f32_e32 v2, v2
	v_readlane_b32 s5, v242, 53
	s_mov_b64 s[6:7], -1
	v_mul_f32_e32 v2, 0x4f7ffffe, v2
	v_cvt_u32_f32_e32 v2, v2
	v_mul_lo_u32 v3, v3, v2
	v_mul_hi_u32 v3, v2, v3
	v_add_u32_e32 v2, v2, v3
	v_mul_hi_u32 v2, v1, v2
	v_mul_lo_u32 v3, v2, v0
	v_sub_u32_e32 v3, v1, v3
	v_cmp_ge_u32_e32 vcc, v3, v0
	v_add_u32_e32 v4, 1, v2
	v_add_u32_e32 v1, 1, v1
	v_cndmask_b32_e32 v2, v2, v4, vcc
	v_sub_u32_e32 v4, v3, v0
	v_cndmask_b32_e32 v3, v3, v4, vcc
	v_cmp_ge_u32_e32 vcc, v3, v0
	v_add_u32_e32 v3, 1, v2
	s_nop 0
	v_cndmask_b32_e32 v2, v2, v3, vcc
	v_mul_lo_u32 v3, v0, v2
	v_add_u32_e32 v0, v3, v0
	v_cmp_ne_u32_e32 vcc, v1, v0
	v_mov_b64_e32 v[0:1], s[4:5]
	s_and_saveexec_b64 s[4:5], vcc
	s_cbranch_execz .LBB0_1422
	v_readlane_b32 s6, v242, 52
	v_readlane_b32 s7, v242, 53
	s_mov_b64 s[8:9], 0
	s_nop 3
	global_load_dword v0, v[142:143], off sc1
	s_waitcnt vmcnt(0)
	v_cmp_eq_u32_e32 vcc, v0, v2
	s_and_saveexec_b64 s[6:7], vcc
	s_cbranch_execz .LBB0_1421
	s_mov_b32 s1, 1
	s_branch .LBB0_1414

.LBB0_1416:
	v_readlane_b32 s12, v242, 52
	v_readlane_b32 s13, v242, 53
	s_add_i32 s1, s1, 1
	s_mov_b64 s[18:19], -1
	s_nop 2
	global_load_dword v0, v[142:143], off sc1
	s_waitcnt vmcnt(0)
	v_cmp_ne_u32_e32 vcc, v0, v2
	s_orn2_b64 s[14:15], vcc, exec
	s_branch .LBB0_1413

.LBB0_1422:
	s_or_b64 exec, exec, s[4:5]
	s_and_saveexec_b64 s[4:5], s[6:7]
	s_cbranch_execz .LBB0_1424
	v_readlane_b32 s6, v242, 50
	v_readlane_b32 s7, v242, 51
	s_nop 4
	global_atomic_add v129, v166, s[6:7] offset:-4096
	global_atomic_add v129, v166, s[6:7] offset:-3840
	global_atomic_add v129, v166, s[6:7] offset:-3584
	global_atomic_add v129, v166, s[6:7] offset:-3328
	global_atomic_add v129, v166, s[6:7] offset:-3072
	global_atomic_add v129, v166, s[6:7] offset:-2816
	global_atomic_add v129, v166, s[6:7] offset:-2560
	global_atomic_add v129, v166, s[6:7] offset:-2304
	global_atomic_add v129, v166, s[6:7] offset:-2048
	global_atomic_add v129, v166, s[6:7] offset:-1792
	global_atomic_add v129, v166, s[6:7] offset:-1536
	global_atomic_add v129, v166, s[6:7] offset:-1280
	global_atomic_add v129, v166, s[6:7] offset:-1024
	global_atomic_add v129, v166, s[6:7] offset:-768
	global_atomic_add v129, v166, s[6:7] offset:-512
	global_atomic_add v129, v166, s[6:7] offset:-256
.LBB0_1424:
	s_or_b64 exec, exec, s[4:5]
	s_waitcnt vmcnt(0)
	s_waitcnt vmcnt(0)
.LBB0_1425:
	s_or_b64 exec, exec, s[2:3]
	v_readlane_b32 s40, v242, 4
	v_readfirstlane_b32 s15, v139
	v_readfirstlane_b32 s14, v138
	v_readlane_b32 s41, v242, 5
	s_waitcnt lgkmcnt(0)
	s_barrier
	s_add_u32 s1, s14, 0x4000
	s_addc_u32 s2, s15, 0
	s_cmp_lg_u32 s22, 3
	s_cselect_b64 s[42:43], -1, 0
	s_mov_b64 s[44:45], 0
	s_and_b64 vcc, exec, s[42:43]
	s_mov_b64 s[46:47], 0
	s_cbranch_vccz .LBB0_1427
	s_add_i32 s3, s22, 1
	s_lshl_b32 s72, s3, 10
	s_lshl_b64 s[4:5], s[72:73], 2
	v_readlane_b32 s8, v241, 16
	v_readlane_b32 s9, v241, 17
	s_add_u32 s44, s8, s4
	s_mul_i32 s72, s3, 0xd800
	s_addc_u32 s45, s9, s5
	s_lshl_b64 s[4:5], s[72:73], 2
	s_add_u32 s3, s1, s4
	s_addc_u32 s4, s2, s5
	s_add_u32 s46, s3, 0x1000
	s_addc_u32 s47, s4, 0
	v_readlane_b32 s10, v241, 18
	v_readlane_b32 s11, v241, 19

.LBB0_1576:
	s_or_b64 exec, exec, s[2:3]
	s_and_saveexec_b64 s[2:3], s[4:5]
	s_cbranch_execz .Ltramp_270
	v_readlane_b32 s4, v242, 50
	v_readlane_b32 s5, v242, 51
	s_nop 4
	global_atomic_add v129, v166, s[4:5] offset:-4096
	global_atomic_add v129, v166, s[4:5] offset:-3840
	global_atomic_add v129, v166, s[4:5] offset:-3584
	global_atomic_add v129, v166, s[4:5] offset:-3328
	global_atomic_add v129, v166, s[4:5] offset:-3072
	global_atomic_add v129, v166, s[4:5] offset:-2816
	global_atomic_add v129, v166, s[4:5] offset:-2560
	global_atomic_add v129, v166, s[4:5] offset:-2304
	global_atomic_add v129, v166, s[4:5] offset:-2048
	global_atomic_add v129, v166, s[4:5] offset:-1792
	global_atomic_add v129, v166, s[4:5] offset:-1536
	global_atomic_add v129, v166, s[4:5] offset:-1280
	global_atomic_add v129, v166, s[4:5] offset:-1024
	global_atomic_add v129, v166, s[4:5] offset:-768
	global_atomic_add v129, v166, s[4:5] offset:-512
	global_atomic_add v129, v166, s[4:5] offset:-256
	s_branch .Ltramp_270
